# mla_up phase: workgroups with an odd virtual CU index start their tiles 12 us late (s_sleep) so the epilogue traffic bursts of the two halves do not coincide; on top of the G1 epilogue change
# baseline (speedup 1.0000x reference)
; __global__ void __launch_bounds__(512, 2) trunk_fwd(Args a0) {
;     ...
;                 else if (sp == 3 && j == 0) { g.A = PROJ + C_OZ; g.lda = PW; g.Bt = (const bf16_t*)(wb + W_MU); g.ldb = 512; g.N = 1024; g.K = 512; E.kind = K_MLAUP; }
;                 else if (sp == 4 && j == 0) { g.A = (const bf16_t*)(ws + WS_QRAW)  ; g.lda = 1024; g.Bt = (const bf16_t*)(wb + W_O) + (size_t)(l & 1) * 1024 * 1024; g.ldb = 1024; g.N = 1024; g.K = 1024; E.kind = K_OUT; }
;                 else break;
;                 const int rot = (E.kind == K_KV) ? 134 : (E.kind == K_VT) ? 138 : 0;
;                 pg8::StaticOrder S; S.init(g.M, g.N, G, (bx + G - rot % G) % G); pg8::gemm_phase(lds, g, S, E, wv);
.LBB0_247:
	v_readlane_b32 s2, v254, 34
	s_nop 3
	s_bitcmp1_b32 s2, 0
	s_cbranch_scc0 .Lstag_skip247
	s_sleep 127
	s_sleep 127
	s_sleep 127
